# cache policy: bf16 weight stores of the transposes non-temporal
# speedup vs baseline: 1.0035x; 1.0035x over previous
; #define LAS __attribute__((address_space(3)))
; __device__ __forceinline__ void transpose_item(const float* W, int K, int N, bf16_t* WT, LAS float* scr, int item, int lane) {
;     const int nblk = N / 32, kb = item / nblk, nb = item % nblk, k0 = 64 * kb, n0 = 32 * nb;
;     float wv[32];
; #pragma unroll
;     for (int i = 0; i < 32; ++i) wv[i] = W[(size_t)(k0 + 2 * i + (lane >> 5)) * N + n0 + (lane & 31)];
.LBB0_1106:
	s_lshr_b32 s22, s34, 5
	v_cvt_f32_u32_e32 v1, s22
	s_sub_i32 s70, 0, s22
	s_abs_i32 s60, s61
	s_ashr_i32 s23, s61, 31
	v_rcp_iflag_f32_e32 v1, v1
	s_nop 0
	v_mul_f32_e32 v1, 0x4f7ffffe, v1
	v_cvt_u32_f32_e32 v1, v1
	s_nop 0
	v_readfirstlane_b32 s71, v1
	s_mul_i32 s70, s70, s71
	s_mul_hi_u32 s70, s71, s70
	s_add_i32 s71, s71, s70
	s_mul_hi_u32 s70, s60, s71
	s_mul_i32 s71, s70, s22
	s_sub_i32 s60, s60, s71
	s_add_i32 s71, s70, 1
	s_sub_i32 s82, s60, s22
	s_cmp_ge_u32 s60, s22
	s_cselect_b32 s70, s71, s70
	s_cselect_b32 s60, s82, s60
	s_add_i32 s71, s70, 1
	s_cmp_ge_u32 s60, s22
	s_cselect_b32 s60, s71, s70
	s_xor_b32 s60, s60, s23
	s_sub_i32 s23, s60, s23
	s_mul_i32 s22, s23, s22
	s_sub_i32 s60, s61, s22
	s_lshl_b32 s60, s60, 5
	s_ashr_i32 s61, s60, 31
	s_lshl_b32 s22, s23, 6
	s_lshl_b64 s[70:71], s[60:61], 2
	s_add_u32 s70, s78, s70
	v_or_b32_e32 v1, s22, v4
	s_addc_u32 s71, s79, s71
	s_ashr_i32 s23, s22, 31
	v_lshl_add_u64 v[2:3], s[70:71], 0, v[96:97]
	s_mul_i32 s78, s23, s34
	v_mad_u64_u32 v[12:13], s[70:71], v1, s34, 0
	v_add_u32_e32 v13, s78, v13
	v_lshl_add_u64 v[12:13], v[12:13], 2, v[2:3]
	global_load_dword v11, v[12:13], off nt
	v_or_b32_e32 v12, 2, v1
	v_mad_u64_u32 v[12:13], s[70:71], v12, s34, 0
	v_add_u32_e32 v13, s78, v13
	v_lshl_add_u64 v[12:13], v[12:13], 2, v[2:3]
	global_load_dword v14, v[12:13], off nt
	v_or_b32_e32 v12, 4, v1
	v_mad_u64_u32 v[12:13], s[70:71], v12, s34, 0
	v_add_u32_e32 v13, s78, v13
	v_lshl_add_u64 v[12:13], v[12:13], 2, v[2:3]
	global_load_dword v15, v[12:13], off nt
	v_or_b32_e32 v12, 6, v1
	v_mad_u64_u32 v[12:13], s[70:71], v12, s34, 0
	v_add_u32_e32 v13, s78, v13
	v_lshl_add_u64 v[12:13], v[12:13], 2, v[2:3]
	global_load_dword v16, v[12:13], off nt
	v_or_b32_e32 v12, 8, v1
	v_mad_u64_u32 v[12:13], s[70:71], v12, s34, 0
	v_add_u32_e32 v13, s78, v13
	v_lshl_add_u64 v[12:13], v[12:13], 2, v[2:3]
	global_load_dword v17, v[12:13], off nt
	v_or_b32_e32 v12, 10, v1
	v_mad_u64_u32 v[12:13], s[70:71], v12, s34, 0
	v_add_u32_e32 v13, s78, v13
	v_lshl_add_u64 v[12:13], v[12:13], 2, v[2:3]
	global_load_dword v18, v[12:13], off nt
	v_or_b32_e32 v12, 12, v1
	v_mad_u64_u32 v[12:13], s[70:71], v12, s34, 0
	v_add_u32_e32 v13, s78, v13
	v_lshl_add_u64 v[12:13], v[12:13], 2, v[2:3]
	global_load_dword v19, v[12:13], off nt
	v_or_b32_e32 v12, 14, v1
	v_mad_u64_u32 v[12:13], s[70:71], v12, s34, 0
	v_add_u32_e32 v13, s78, v13
	v_lshl_add_u64 v[12:13], v[12:13], 2, v[2:3]
	global_load_dword v20, v[12:13], off nt
	v_or_b32_e32 v12, 16, v1
	v_mad_u64_u32 v[12:13], s[70:71], v12, s34, 0
	v_add_u32_e32 v13, s78, v13
	v_lshl_add_u64 v[12:13], v[12:13], 2, v[2:3]
	global_load_dword v21, v[12:13], off nt
	v_or_b32_e32 v12, 18, v1
	v_mad_u64_u32 v[12:13], s[70:71], v12, s34, 0
	v_add_u32_e32 v13, s78, v13
	v_lshl_add_u64 v[12:13], v[12:13], 2, v[2:3]
	global_load_dword v22, v[12:13], off nt
	v_or_b32_e32 v12, 20, v1
	v_mad_u64_u32 v[12:13], s[70:71], v12, s34, 0
	v_add_u32_e32 v13, s78, v13
	v_lshl_add_u64 v[12:13], v[12:13], 2, v[2:3]
	global_load_dword v23, v[12:13], off nt
	v_or_b32_e32 v12, 22, v1
	v_mad_u64_u32 v[12:13], s[70:71], v12, s34, 0
	v_add_u32_e32 v13, s78, v13
	v_lshl_add_u64 v[12:13], v[12:13], 2, v[2:3]
	global_load_dword v24, v[12:13], off nt
	v_or_b32_e32 v12, 24, v1
	v_mad_u64_u32 v[12:13], s[70:71], v12, s34, 0
	v_add_u32_e32 v13, s78, v13
	v_lshl_add_u64 v[12:13], v[12:13], 2, v[2:3]
	global_load_dword v25, v[12:13], off nt
	v_or_b32_e32 v12, 26, v1
	v_mad_u64_u32 v[12:13], s[70:71], v12, s34, 0
	v_add_u32_e32 v13, s78, v13
	v_lshl_add_u64 v[12:13], v[12:13], 2, v[2:3]
	global_load_dword v26, v[12:13], off nt
	v_or_b32_e32 v12, 28, v1
	v_mad_u64_u32 v[12:13], s[70:71], v12, s34, 0
	v_add_u32_e32 v13, s78, v13
	v_lshl_add_u64 v[12:13], v[12:13], 2, v[2:3]
	global_load_dword v27, v[12:13], off nt
	v_or_b32_e32 v12, 30, v1
	v_mad_u64_u32 v[12:13], s[70:71], v12, s34, 0
	v_add_u32_e32 v13, s78, v13
	v_lshl_add_u64 v[12:13], v[12:13], 2, v[2:3]
	global_load_dword v28, v[12:13], off nt
	v_or_b32_e32 v12, 32, v1
	v_mad_u64_u32 v[12:13], s[70:71], v12, s34, 0
	v_add_u32_e32 v13, s78, v13
	v_lshl_add_u64 v[12:13], v[12:13], 2, v[2:3]
	global_load_dword v29, v[12:13], off nt
	v_or_b32_e32 v12, 34, v1
	v_mad_u64_u32 v[12:13], s[70:71], v12, s34, 0
	v_add_u32_e32 v13, s78, v13
	v_lshl_add_u64 v[12:13], v[12:13], 2, v[2:3]
	global_load_dword v30, v[12:13], off nt
	v_or_b32_e32 v12, 36, v1
	v_mad_u64_u32 v[12:13], s[70:71], v12, s34, 0
	v_add_u32_e32 v13, s78, v13
	v_lshl_add_u64 v[12:13], v[12:13], 2, v[2:3]
	global_load_dword v31, v[12:13], off nt
	v_or_b32_e32 v12, 38, v1
	v_mad_u64_u32 v[12:13], s[70:71], v12, s34, 0
	v_add_u32_e32 v13, s78, v13
	v_lshl_add_u64 v[12:13], v[12:13], 2, v[2:3]
	global_load_dword v32, v[12:13], off nt
	v_or_b32_e32 v12, 40, v1
	v_mad_u64_u32 v[12:13], s[70:71], v12, s34, 0
	v_add_u32_e32 v13, s78, v13
	v_lshl_add_u64 v[12:13], v[12:13], 2, v[2:3]
	global_load_dword v33, v[12:13], off nt
	v_or_b32_e32 v12, 42, v1
	v_mad_u64_u32 v[12:13], s[70:71], v12, s34, 0
	v_add_u32_e32 v13, s78, v13
	v_lshl_add_u64 v[12:13], v[12:13], 2, v[2:3]
	global_load_dword v34, v[12:13], off nt
	v_or_b32_e32 v12, 44, v1
	v_mad_u64_u32 v[12:13], s[70:71], v12, s34, 0
	v_add_u32_e32 v13, s78, v13
	v_lshl_add_u64 v[12:13], v[12:13], 2, v[2:3]
	global_load_dword v35, v[12:13], off nt
	v_or_b32_e32 v12, 46, v1
	v_mad_u64_u32 v[12:13], s[70:71], v12, s34, 0
	v_add_u32_e32 v13, s78, v13
	v_lshl_add_u64 v[12:13], v[12:13], 2, v[2:3]
	global_load_dword v36, v[12:13], off nt
	v_or_b32_e32 v12, 48, v1
	v_mad_u64_u32 v[12:13], s[70:71], v12, s34, 0
	v_add_u32_e32 v13, s78, v13
	v_lshl_add_u64 v[12:13], v[12:13], 2, v[2:3]
; #define LAS __attribute__((address_space(3)))
; __device__ __forceinline__ unsigned pk2(float lo, float hi) { return f2bf(lo) | (f2bf(hi) << 16); }
; __device__ __forceinline__ void transpose_item(const float* W, int K, int N, bf16_t* WT, LAS float* scr, int item, int lane) {
;     ...
;     for (int i = 0; i < 32; ++i) wv[i] = W[(size_t)(k0 + 2 * i + (lane >> 5)) * N + n0 + (lane & 31)];
; #pragma unroll
;     for (int i = 0; i < 32; ++i) scr[(2 * i + (lane >> 5)) * 33 + (lane & 31)] = wv[i];
;     asm volatile("s_waitcnt lgkmcnt(0)" ::: "memory");
;     const int c = lane & 7;
; #pragma unroll
;     for (int j = 0; j < 4; ++j) { const int n = (lane >> 3) + 8 * j; const LAS float* s = scr + (8 * c) * 33 + n;
;         u32x4 o; o.x = pk2(s[0 * 33], s[1 * 33]); o.y = pk2(s[2 * 33], s[3 * 33]); o.z = pk2(s[4 * 33], s[5 * 33]); o.w = pk2(s[6 * 33], s[7 * 33]);
	global_load_dword v37, v[12:13], off nt
	v_or_b32_e32 v12, 50, v1
	v_mad_u64_u32 v[12:13], s[70:71], v12, s34, 0
	v_add_u32_e32 v13, s78, v13
	v_lshl_add_u64 v[12:13], v[12:13], 2, v[2:3]
	global_load_dword v38, v[12:13], off nt
	v_or_b32_e32 v12, 52, v1
	v_mad_u64_u32 v[12:13], s[70:71], v12, s34, 0
	v_add_u32_e32 v13, s78, v13
	v_lshl_add_u64 v[12:13], v[12:13], 2, v[2:3]
	global_load_dword v39, v[12:13], off nt
	v_or_b32_e32 v12, 54, v1
	v_mad_u64_u32 v[12:13], s[70:71], v12, s34, 0
	v_add_u32_e32 v13, s78, v13
	v_lshl_add_u64 v[12:13], v[12:13], 2, v[2:3]
	global_load_dword v40, v[12:13], off nt
	v_or_b32_e32 v12, 56, v1
	v_mad_u64_u32 v[12:13], s[70:71], v12, s34, 0
	v_add_u32_e32 v13, s78, v13
	v_lshl_add_u64 v[12:13], v[12:13], 2, v[2:3]
	global_load_dword v41, v[12:13], off nt
	v_or_b32_e32 v12, 58, v1
	v_mad_u64_u32 v[12:13], s[70:71], v12, s34, 0
	v_add_u32_e32 v13, s78, v13
	v_lshl_add_u64 v[12:13], v[12:13], 2, v[2:3]
	global_load_dword v42, v[12:13], off nt
	v_or_b32_e32 v12, 60, v1
	v_mad_u64_u32 v[12:13], s[70:71], v12, s34, 0
	v_add_u32_e32 v13, s78, v13
	v_lshl_add_u64 v[12:13], v[12:13], 2, v[2:3]
	v_or_b32_e32 v1, 62, v1
	global_load_dword v43, v[12:13], off nt
	v_mad_u64_u32 v[12:13], s[70:71], v1, s34, 0
	v_add_u32_e32 v13, s78, v13
	v_lshl_add_u64 v[2:3], v[12:13], 2, v[2:3]
	global_load_dword v1, v[2:3], off nt
	v_add_u32_e32 v2, 0x400, v10
	s_waitcnt vmcnt(0)
	ds_write2_b32 v10, v11, v14 offset1:66
	ds_write2_b32 v10, v15, v16 offset0:132 offset1:198
	ds_write2_b32 v2, v17, v18 offset0:8 offset1:74
	ds_write2_b32 v2, v19, v20 offset0:140 offset1:206
	v_add_u32_e32 v2, 0x800, v10
	ds_write2_b32 v2, v21, v22 offset0:16 offset1:82
	ds_write2_b32 v2, v23, v24 offset0:148 offset1:214
	v_add_u32_e32 v2, 0xc00, v10
	ds_write2_b32 v2, v25, v26 offset0:24 offset1:90
	ds_write2_b32 v2, v27, v28 offset0:156 offset1:222
	v_add_u32_e32 v2, 0x1000, v10
	ds_write2_b32 v2, v29, v30 offset0:32 offset1:98
	ds_write2_b32 v2, v31, v32 offset0:164 offset1:230
	v_add_u32_e32 v2, 0x1400, v10
	ds_write2_b32 v2, v33, v34 offset0:40 offset1:106
	ds_write2_b32 v2, v35, v36 offset0:172 offset1:238
	v_add_u32_e32 v2, 0x1800, v10
	ds_write2_b32 v2, v37, v38 offset0:48 offset1:114
	ds_write2_b32 v2, v39, v40 offset0:180 offset1:246
	v_add_u32_e32 v2, 0x1c00, v10
	ds_write2_b32 v2, v41, v42 offset0:56 offset1:122
	ds_write2_b32 v2, v43, v1 offset0:188 offset1:254
	s_waitcnt lgkmcnt(0)
	ds_read2_b32 v[16:17], v6 offset0:33 offset1:41
	ds_read2_b32 v[18:19], v6 offset1:8
	s_lshl_b64 s[22:23], s[22:23], 1
	s_add_u32 s22, s76, s22
	s_addc_u32 s23, s77, s23
	v_mov_b32_e32 v1, v97
	ds_read2_b32 v[20:21], v6 offset0:66 offset1:74
	ds_read2_b32 v[22:23], v6 offset0:99 offset1:107
	v_lshl_add_u64 v[2:3], s[22:23], 0, v[0:1]
	s_waitcnt lgkmcnt(2)
	v_bfe_u32 v1, v18, 16, 1
	v_add3_u32 v1, v18, v1, s28
	v_bfe_u32 v11, v16, 16, 1
	v_lshrrev_b32_e32 v1, 16, v1
	v_add3_u32 v11, v16, v11, s28
	ds_read2_b32 v[24:25], v6 offset0:132 offset1:140
	ds_read2_b32 v[26:27], v6 offset0:165 offset1:173
	v_and_or_b32 v12, v11, s39, v1
	s_waitcnt lgkmcnt(3)
	v_bfe_u32 v1, v20, 16, 1
	v_add3_u32 v1, v20, v1, s28
	s_waitcnt lgkmcnt(2)
	v_bfe_u32 v11, v22, 16, 1
	v_lshrrev_b32_e32 v1, 16, v1
	v_add3_u32 v11, v22, v11, s28
	ds_read2_b32 v[28:29], v6 offset0:198 offset1:206
	ds_read2_b32 v[30:31], v6 offset0:231 offset1:239
	v_and_or_b32 v13, v11, s39, v1
	s_waitcnt lgkmcnt(3)
	v_bfe_u32 v1, v24, 16, 1
	v_add3_u32 v1, v24, v1, s28
	s_waitcnt lgkmcnt(2)
	v_bfe_u32 v11, v26, 16, 1
	v_lshrrev_b32_e32 v1, 16, v1
	v_add3_u32 v11, v26, v11, s28
	v_and_or_b32 v14, v11, s39, v1
	s_waitcnt lgkmcnt(1)
	v_bfe_u32 v1, v28, 16, 1
	v_add3_u32 v1, v28, v1, s28
	s_waitcnt lgkmcnt(0)
; #define LAS __attribute__((address_space(3)))
; __device__ __forceinline__ unsigned pk2(float lo, float hi) { return f2bf(lo) | (f2bf(hi) << 16); }
; __device__ __forceinline__ void transpose_item(const float* W, int K, int N, bf16_t* WT, LAS float* scr, int item, int lane) {
;     ...
;     for (int j = 0; j < 4; ++j) { const int n = (lane >> 3) + 8 * j; const LAS float* s = scr + (8 * c) * 33 + n;
;         u32x4 o; o.x = pk2(s[0 * 33], s[1 * 33]); o.y = pk2(s[2 * 33], s[3 * 33]); o.z = pk2(s[4 * 33], s[5 * 33]); o.w = pk2(s[6 * 33], s[7 * 33]);
;         *(u32x4*)(WT + (size_t)(n0 + n) * K + k0 + 8 * c) = o; }
;     asm volatile("s_waitcnt lgkmcnt(0)" ::: "memory");
	v_bfe_u32 v11, v30, 16, 1
	v_lshrrev_b32_e32 v1, 16, v1
	v_add3_u32 v11, v30, v11, s28
	v_and_or_b32 v15, v11, s39, v1
	v_or_b32_e32 v1, s60, v5
	v_mad_u64_u32 v[32:33], s[22:23], s58, v1, 0
	v_mul_lo_u32 v11, s59, v1
	s_mul_i32 s22, s58, s61
	v_bfe_u32 v1, v19, 16, 1
	v_add3_u32 v33, v33, s22, v11
	v_add3_u32 v1, v19, v1, s28
	v_bfe_u32 v11, v17, 16, 1
	v_lshl_add_u64 v[32:33], v[32:33], 1, v[2:3]
	v_lshrrev_b32_e32 v1, 16, v1
	v_add3_u32 v11, v17, v11, s28
	global_store_dwordx4 v[32:33], v[12:15], off nt
	s_add_i32 s81, s81, s73
	s_add_i32 s69, s69, s73
	v_and_or_b32 v12, v11, s39, v1
	v_bfe_u32 v1, v21, 16, 1
	v_add3_u32 v1, v21, v1, s28
	v_bfe_u32 v11, v23, 16, 1
	v_lshrrev_b32_e32 v1, 16, v1
	v_add3_u32 v11, v23, v11, s28
	v_and_or_b32 v13, v11, s39, v1
	v_bfe_u32 v1, v25, 16, 1
	v_add3_u32 v1, v25, v1, s28
	v_bfe_u32 v11, v27, 16, 1
	v_lshrrev_b32_e32 v1, 16, v1
	v_add3_u32 v11, v27, v11, s28
	v_and_or_b32 v14, v11, s39, v1
	v_bfe_u32 v1, v29, 16, 1
	v_add3_u32 v1, v29, v1, s28
	v_bfe_u32 v11, v31, 16, 1
	v_lshrrev_b32_e32 v1, 16, v1
	v_add3_u32 v11, v31, v11, s28
	v_and_or_b32 v15, v11, s39, v1
	v_or_b32_e32 v1, s60, v7
	v_mul_lo_u32 v11, s59, v1
	v_mad_u64_u32 v[16:17], s[70:71], s58, v1, 0
	v_add3_u32 v17, v17, s22, v11
	v_lshl_add_u64 v[16:17], v[16:17], 1, v[2:3]
	global_store_dwordx4 v[16:17], v[12:15], off nt
	ds_read2_b32 v[16:17], v6 offset0:16 offset1:24
	ds_read2_b32 v[18:19], v6 offset0:49 offset1:57
	ds_read2_b32 v[20:21], v6 offset0:82 offset1:90
	ds_read2_b32 v[22:23], v6 offset0:115 offset1:123
	ds_read2_b32 v[24:25], v6 offset0:148 offset1:156
	ds_read2_b32 v[26:27], v6 offset0:181 offset1:189
	ds_read2_b32 v[28:29], v6 offset0:214 offset1:222
	ds_read2_b32 v[30:31], v6 offset0:247 offset1:255
	s_waitcnt lgkmcnt(7)
	v_bfe_u32 v1, v16, 16, 1
	v_add3_u32 v1, v16, v1, s28
	s_waitcnt lgkmcnt(6)
	v_bfe_u32 v11, v18, 16, 1
	v_lshrrev_b32_e32 v1, 16, v1
	v_add3_u32 v11, v18, v11, s28
	v_and_or_b32 v12, v11, s39, v1
	s_waitcnt lgkmcnt(5)
	v_bfe_u32 v1, v20, 16, 1
	v_add3_u32 v1, v20, v1, s28
	s_waitcnt lgkmcnt(4)
	v_bfe_u32 v11, v22, 16, 1
	v_lshrrev_b32_e32 v1, 16, v1
	v_add3_u32 v11, v22, v11, s28
	v_and_or_b32 v13, v11, s39, v1
	s_waitcnt lgkmcnt(3)
	v_bfe_u32 v1, v24, 16, 1
	v_add3_u32 v1, v24, v1, s28
	s_waitcnt lgkmcnt(2)
	v_bfe_u32 v11, v26, 16, 1
	v_lshrrev_b32_e32 v1, 16, v1
	v_add3_u32 v11, v26, v11, s28
	v_and_or_b32 v14, v11, s39, v1
	s_waitcnt lgkmcnt(1)
	v_bfe_u32 v1, v28, 16, 1
	v_add3_u32 v1, v28, v1, s28
	s_waitcnt lgkmcnt(0)
	v_bfe_u32 v11, v30, 16, 1
	v_lshrrev_b32_e32 v1, 16, v1
	v_add3_u32 v11, v30, v11, s28
	v_and_or_b32 v15, v11, s39, v1
	v_or_b32_e32 v1, s60, v8
	v_mul_lo_u32 v11, s59, v1
	v_mad_u64_u32 v[32:33], s[70:71], s58, v1, 0
	v_bfe_u32 v1, v17, 16, 1
	v_add3_u32 v33, v33, s22, v11
	v_add3_u32 v1, v17, v1, s28
	v_bfe_u32 v11, v19, 16, 1
	v_lshl_add_u64 v[32:33], v[32:33], 1, v[2:3]
	v_lshrrev_b32_e32 v1, 16, v1
	v_add3_u32 v11, v19, v11, s28
	global_store_dwordx4 v[32:33], v[12:15], off nt
	s_add_i32 s74, s74, s73
	s_add_i32 s75, s75, s73
	v_and_or_b32 v12, v11, s39, v1
	v_bfe_u32 v1, v21, 16, 1
	v_add3_u32 v1, v21, v1, s28
	v_bfe_u32 v11, v23, 16, 1
	v_lshrrev_b32_e32 v1, 16, v1
	v_add3_u32 v11, v23, v11, s28
	v_and_or_b32 v13, v11, s39, v1
	v_bfe_u32 v1, v25, 16, 1
	v_add3_u32 v1, v25, v1, s28
	v_bfe_u32 v11, v27, 16, 1
	v_lshrrev_b32_e32 v1, 16, v1
	v_add3_u32 v11, v27, v11, s28
	v_and_or_b32 v14, v11, s39, v1
	v_bfe_u32 v1, v29, 16, 1
	v_add3_u32 v1, v29, v1, s28
	v_bfe_u32 v11, v31, 16, 1
	v_lshrrev_b32_e32 v1, 16, v1
	v_add3_u32 v11, v31, v11, s28
	v_and_or_b32 v15, v11, s39, v1
	v_or_b32_e32 v1, s60, v9
	v_mul_lo_u32 v11, s59, v1
	v_mad_u64_u32 v[16:17], s[58:59], s58, v1, 0
	v_add3_u32 v17, v17, s22, v11
	v_lshl_add_u64 v[2:3], v[16:17], 1, v[2:3]
	global_store_dwordx4 v[2:3], v[12:15], off nt
	s_waitcnt lgkmcnt(0)
	s_sub_i32 s22, s37, s44
	s_add_i32 s37, s22, 0x800
	s_add_i32 s80, s80, s73
	s_add_i32 s22, s89, s81
	s_cmp_ge_i32 s22, s38
	s_movk_i32 s82, 0x2000
	s_cbranch_scc1 .LBB0_1154

; #define LAS __attribute__((address_space(3)))
; __device__ __forceinline__ void transpose_item(const float* W, int K, int N, bf16_t* WT, LAS float* scr, int item, int lane) {
;     const int nblk = N / 32, kb = item / nblk, nb = item % nblk, k0 = 64 * kb, n0 = 32 * nb;
;     float wv[32];
; #pragma unroll
;     for (int i = 0; i < 32; ++i) wv[i] = W[(size_t)(k0 + 2 * i + (lane >> 5)) * N + n0 + (lane & 31)];
.LBB0_1170:
	s_lshr_b32 s22, s34, 5
	v_cvt_f32_u32_e32 v1, s22
	s_sub_i32 s44, 0, s22
	s_abs_i32 s37, s38
	s_ashr_i32 s23, s38, 31
	v_rcp_iflag_f32_e32 v1, v1
	s_nop 0
	v_mul_f32_e32 v1, 0x4f7ffffe, v1
	v_cvt_u32_f32_e32 v1, v1
	s_nop 0
	v_readfirstlane_b32 s45, v1
	s_mul_i32 s44, s44, s45
	s_mul_hi_u32 s44, s45, s44
	s_add_i32 s45, s45, s44
	s_mul_hi_u32 s44, s37, s45
	s_mul_i32 s45, s44, s22
	s_sub_i32 s37, s37, s45
	s_add_i32 s46, s44, 1
	s_sub_i32 s45, s37, s22
	s_cmp_ge_u32 s37, s22
	s_cselect_b32 s44, s46, s44
	s_cselect_b32 s37, s45, s37
	s_add_i32 s45, s44, 1
	s_cmp_ge_u32 s37, s22
	s_cselect_b32 s37, s45, s44
	s_xor_b32 s37, s37, s23
	s_sub_i32 s23, s37, s23
	s_mul_i32 s22, s23, s22
	s_sub_i32 s22, s38, s22
	s_lshl_b32 s22, s22, 5
	s_lshl_b32 s72, s23, 6
	s_ashr_i32 s23, s22, 31
	s_lshl_b64 s[44:45], s[22:23], 2
	v_or_b32_e32 v1, s72, v2
	s_waitcnt lgkmcnt(0)
	s_add_u32 s44, s70, s44
	s_addc_u32 s45, s71, s45
	v_or_b32_e32 v11, 2, v1
	v_lshl_add_u64 v[12:13], s[44:45], 0, v[96:97]
	v_mad_u64_u32 v[16:17], s[44:45], v11, s34, 0
	v_or_b32_e32 v11, 4, v1
	v_mad_u64_u32 v[18:19], s[44:45], v11, s34, 0
	v_or_b32_e32 v11, 6, v1
	v_mad_u64_u32 v[20:21], s[44:45], v11, s34, 0
	v_or_b32_e32 v11, 8, v1
	v_mad_u64_u32 v[22:23], s[44:45], v11, s34, 0
	v_or_b32_e32 v11, 10, v1
	s_ashr_i32 s73, s72, 31
	v_mad_u64_u32 v[24:25], s[44:45], v11, s34, 0
	v_or_b32_e32 v11, 12, v1
	s_mul_i32 s37, s73, s34
	v_mad_u64_u32 v[14:15], s[44:45], v1, s34, 0
	v_mad_u64_u32 v[26:27], s[44:45], v11, s34, 0
	v_or_b32_e32 v11, 14, v1
	v_add_u32_e32 v15, s37, v15
	v_add_u32_e32 v17, s37, v17
	v_add_u32_e32 v19, s37, v19
	v_add_u32_e32 v21, s37, v21
	v_add_u32_e32 v23, s37, v23
	v_add_u32_e32 v25, s37, v25
	v_add_u32_e32 v27, s37, v27
	s_waitcnt vmcnt(0)
	v_mad_u64_u32 v[28:29], s[44:45], v11, s34, 0
	v_lshl_add_u64 v[14:15], v[14:15], 2, v[12:13]
	v_lshl_add_u64 v[16:17], v[16:17], 2, v[12:13]
	v_lshl_add_u64 v[18:19], v[18:19], 2, v[12:13]
	v_lshl_add_u64 v[20:21], v[20:21], 2, v[12:13]
	v_lshl_add_u64 v[22:23], v[22:23], 2, v[12:13]
	v_lshl_add_u64 v[24:25], v[24:25], 2, v[12:13]
	v_lshl_add_u64 v[26:27], v[26:27], 2, v[12:13]
	v_add_u32_e32 v29, s37, v29
	v_lshl_add_u64 v[28:29], v[28:29], 2, v[12:13]
	global_load_dword v11, v[14:15], off nt
	global_load_dword v30, v[16:17], off nt
	global_load_dword v31, v[18:19], off nt
	global_load_dword v32, v[20:21], off nt
	global_load_dword v33, v[22:23], off nt
	global_load_dword v34, v[24:25], off nt
	global_load_dword v35, v[26:27], off nt
	global_load_dword v36, v[28:29], off nt
	v_or_b32_e32 v14, 16, v1
	v_or_b32_e32 v16, 18, v1
	v_or_b32_e32 v18, 20, v1
	v_or_b32_e32 v20, 22, v1
	v_or_b32_e32 v22, 24, v1
	v_or_b32_e32 v24, 26, v1
	v_or_b32_e32 v26, 28, v1
	v_mad_u64_u32 v[14:15], s[44:45], v14, s34, 0
	v_mad_u64_u32 v[16:17], s[44:45], v16, s34, 0
	v_mad_u64_u32 v[18:19], s[44:45], v18, s34, 0
	v_mad_u64_u32 v[20:21], s[44:45], v20, s34, 0
	v_mad_u64_u32 v[22:23], s[44:45], v22, s34, 0
	v_mad_u64_u32 v[24:25], s[44:45], v24, s34, 0
	v_mad_u64_u32 v[26:27], s[44:45], v26, s34, 0
	v_or_b32_e32 v28, 30, v1
	v_add_u32_e32 v15, s37, v15
	v_add_u32_e32 v17, s37, v17
	v_add_u32_e32 v19, s37, v19
	v_add_u32_e32 v21, s37, v21
	v_add_u32_e32 v23, s37, v23
	v_add_u32_e32 v25, s37, v25
	v_add_u32_e32 v27, s37, v27
	v_mad_u64_u32 v[28:29], s[44:45], v28, s34, 0
	v_lshl_add_u64 v[14:15], v[14:15], 2, v[12:13]
	v_lshl_add_u64 v[16:17], v[16:17], 2, v[12:13]
	v_lshl_add_u64 v[18:19], v[18:19], 2, v[12:13]
	v_lshl_add_u64 v[20:21], v[20:21], 2, v[12:13]
	v_lshl_add_u64 v[22:23], v[22:23], 2, v[12:13]
	v_lshl_add_u64 v[24:25], v[24:25], 2, v[12:13]
	v_lshl_add_u64 v[26:27], v[26:27], 2, v[12:13]
	v_add_u32_e32 v29, s37, v29
	v_lshl_add_u64 v[28:29], v[28:29], 2, v[12:13]
	global_load_dword v37, v[14:15], off nt
	global_load_dword v38, v[16:17], off nt
	global_load_dword v39, v[18:19], off nt
	global_load_dword v40, v[20:21], off nt
	global_load_dword v41, v[22:23], off nt
	global_load_dword v42, v[24:25], off nt
	global_load_dword v43, v[26:27], off nt
	global_load_dword v44, v[28:29], off nt
	v_or_b32_e32 v14, 32, v1
	v_or_b32_e32 v16, 34, v1
	v_or_b32_e32 v18, 36, v1
	v_or_b32_e32 v20, 38, v1
	v_or_b32_e32 v22, 40, v1
	v_or_b32_e32 v24, 42, v1
	v_or_b32_e32 v26, 44, v1
	v_mad_u64_u32 v[14:15], s[44:45], v14, s34, 0
	v_mad_u64_u32 v[16:17], s[44:45], v16, s34, 0
	v_mad_u64_u32 v[18:19], s[44:45], v18, s34, 0
	v_mad_u64_u32 v[20:21], s[44:45], v20, s34, 0
	v_mad_u64_u32 v[22:23], s[44:45], v22, s34, 0
	v_mad_u64_u32 v[24:25], s[44:45], v24, s34, 0
	v_mad_u64_u32 v[26:27], s[44:45], v26, s34, 0
	v_or_b32_e32 v28, 46, v1
	v_add_u32_e32 v15, s37, v15
	v_add_u32_e32 v17, s37, v17
	v_add_u32_e32 v19, s37, v19
	v_add_u32_e32 v21, s37, v21
	v_add_u32_e32 v23, s37, v23
	v_add_u32_e32 v25, s37, v25
	v_add_u32_e32 v27, s37, v27
	v_mad_u64_u32 v[28:29], s[44:45], v28, s34, 0
	v_lshl_add_u64 v[14:15], v[14:15], 2, v[12:13]
	v_lshl_add_u64 v[16:17], v[16:17], 2, v[12:13]
	v_lshl_add_u64 v[18:19], v[18:19], 2, v[12:13]
	v_lshl_add_u64 v[20:21], v[20:21], 2, v[12:13]
	v_lshl_add_u64 v[22:23], v[22:23], 2, v[12:13]
	v_lshl_add_u64 v[24:25], v[24:25], 2, v[12:13]
	v_lshl_add_u64 v[26:27], v[26:27], 2, v[12:13]
	v_add_u32_e32 v29, s37, v29
	v_lshl_add_u64 v[28:29], v[28:29], 2, v[12:13]
	global_load_dword v45, v[14:15], off nt
	global_load_dword v46, v[16:17], off nt
	global_load_dword v47, v[18:19], off nt
	global_load_dword v48, v[20:21], off nt
	global_load_dword v49, v[22:23], off nt
	global_load_dword v50, v[24:25], off nt
	global_load_dword v51, v[26:27], off nt
	global_load_dword v52, v[28:29], off nt
	v_or_b32_e32 v14, 48, v1
; #define LAS __attribute__((address_space(3)))
; __device__ __forceinline__ unsigned pk2(float lo, float hi) { return f2bf(lo) | (f2bf(hi) << 16); }
; __device__ __forceinline__ void transpose_item(const float* W, int K, int N, bf16_t* WT, LAS float* scr, int item, int lane) {
;     ...
;     for (int i = 0; i < 32; ++i) wv[i] = W[(size_t)(k0 + 2 * i + (lane >> 5)) * N + n0 + (lane & 31)];
; #pragma unroll
;     for (int i = 0; i < 32; ++i) scr[(2 * i + (lane >> 5)) * 33 + (lane & 31)] = wv[i];
;     asm volatile("s_waitcnt lgkmcnt(0)" ::: "memory");
;     const int c = lane & 7;
; #pragma unroll
;     for (int j = 0; j < 4; ++j) { const int n = (lane >> 3) + 8 * j; const LAS float* s = scr + (8 * c) * 33 + n;
;         u32x4 o; o.x = pk2(s[0 * 33], s[1 * 33]); o.y = pk2(s[2 * 33], s[3 * 33]); o.z = pk2(s[4 * 33], s[5 * 33]); o.w = pk2(s[6 * 33], s[7 * 33]);
	v_or_b32_e32 v16, 50, v1
	v_or_b32_e32 v18, 52, v1
	v_or_b32_e32 v20, 54, v1
	v_or_b32_e32 v22, 56, v1
	v_or_b32_e32 v24, 58, v1
	v_or_b32_e32 v26, 60, v1
	v_or_b32_e32 v1, 62, v1
	v_mad_u64_u32 v[14:15], s[44:45], v14, s34, 0
	v_mad_u64_u32 v[16:17], s[44:45], v16, s34, 0
	v_mad_u64_u32 v[18:19], s[44:45], v18, s34, 0
	v_mad_u64_u32 v[20:21], s[44:45], v20, s34, 0
	v_mad_u64_u32 v[22:23], s[44:45], v22, s34, 0
	v_mad_u64_u32 v[24:25], s[44:45], v24, s34, 0
	v_mad_u64_u32 v[26:27], s[44:45], v26, s34, 0
	v_mad_u64_u32 v[28:29], s[44:45], v1, s34, 0
	v_add_u32_e32 v15, s37, v15
	v_add_u32_e32 v17, s37, v17
	v_add_u32_e32 v19, s37, v19
	v_add_u32_e32 v21, s37, v21
	v_add_u32_e32 v23, s37, v23
	v_add_u32_e32 v25, s37, v25
	v_add_u32_e32 v27, s37, v27
	v_add_u32_e32 v29, s37, v29
	v_lshl_add_u64 v[14:15], v[14:15], 2, v[12:13]
	v_lshl_add_u64 v[16:17], v[16:17], 2, v[12:13]
	v_lshl_add_u64 v[18:19], v[18:19], 2, v[12:13]
	v_lshl_add_u64 v[20:21], v[20:21], 2, v[12:13]
	v_lshl_add_u64 v[22:23], v[22:23], 2, v[12:13]
	v_lshl_add_u64 v[24:25], v[24:25], 2, v[12:13]
	v_lshl_add_u64 v[26:27], v[26:27], 2, v[12:13]
	v_lshl_add_u64 v[12:13], v[28:29], 2, v[12:13]
	global_load_dword v1, v[14:15], off nt
	s_nop 0
	global_load_dword v14, v[16:17], off nt
	global_load_dword v15, v[18:19], off nt
	s_nop 0
	global_load_dword v16, v[20:21], off nt
	global_load_dword v17, v[22:23], off nt
	global_load_dword v18, v[24:25], off nt
	global_load_dword v19, v[26:27], off nt
	s_nop 0
	global_load_dword v12, v[12:13], off nt
	s_waitcnt vmcnt(30)
	ds_write2_b32 v10, v11, v30 offset1:66
	s_waitcnt vmcnt(28)
	ds_write2_b32 v10, v31, v32 offset0:132 offset1:198
	v_add_u32_e32 v11, 0x400, v10
	s_waitcnt vmcnt(26)
	ds_write2_b32 v11, v33, v34 offset0:8 offset1:74
	s_waitcnt vmcnt(24)
	ds_write2_b32 v11, v35, v36 offset0:140 offset1:206
	v_add_u32_e32 v11, 0x800, v10
	s_waitcnt vmcnt(22)
	ds_write2_b32 v11, v37, v38 offset0:16 offset1:82
	s_waitcnt vmcnt(20)
	ds_write2_b32 v11, v39, v40 offset0:148 offset1:214
	v_add_u32_e32 v11, 0xc00, v10
	s_waitcnt vmcnt(18)
	ds_write2_b32 v11, v41, v42 offset0:24 offset1:90
	s_waitcnt vmcnt(16)
	ds_write2_b32 v11, v43, v44 offset0:156 offset1:222
	v_add_u32_e32 v11, 0x1000, v10
	s_waitcnt vmcnt(14)
	ds_write2_b32 v11, v45, v46 offset0:32 offset1:98
	s_waitcnt vmcnt(12)
	ds_write2_b32 v11, v47, v48 offset0:164 offset1:230
	v_add_u32_e32 v11, 0x1400, v10
	s_waitcnt vmcnt(10)
	ds_write2_b32 v11, v49, v50 offset0:40 offset1:106
	s_waitcnt vmcnt(8)
	ds_write2_b32 v11, v51, v52 offset0:172 offset1:238
	v_add_u32_e32 v11, 0x1800, v10
	s_waitcnt vmcnt(6)
	ds_write2_b32 v11, v1, v14 offset0:48 offset1:114
	s_waitcnt vmcnt(4)
	ds_write2_b32 v11, v15, v16 offset0:180 offset1:246
	v_add_u32_e32 v1, 0x1c00, v10
	s_waitcnt vmcnt(2)
	ds_write2_b32 v1, v17, v18 offset0:56 offset1:122
	s_waitcnt vmcnt(0)
	ds_write2_b32 v1, v19, v12 offset0:188 offset1:254
	s_waitcnt lgkmcnt(0)
	ds_read2_b32 v[16:17], v6 offset1:8
	ds_read2_b32 v[20:21], v6 offset0:33 offset1:41
	s_lshl_b64 s[44:45], s[72:73], 1
	s_add_u32 s44, s60, s44
	ds_read2_b32 v[22:23], v6 offset0:66 offset1:74
	s_addc_u32 s45, s61, s45
	v_mov_b32_e32 v1, v97
	ds_read2_b32 v[24:25], v6 offset0:99 offset1:107
	v_lshl_add_u64 v[18:19], s[44:45], 0, v[0:1]
	s_waitcnt lgkmcnt(3)
	v_bfe_u32 v1, v16, 16, 1
	v_add3_u32 v1, v16, v1, s28
	s_waitcnt lgkmcnt(2)
	v_bfe_u32 v11, v20, 16, 1
	ds_read2_b32 v[26:27], v6 offset0:132 offset1:140
	v_lshrrev_b32_e32 v1, 16, v1
	v_add3_u32 v11, v20, v11, s28
	ds_read2_b32 v[28:29], v6 offset0:165 offset1:173
	v_and_or_b32 v12, v11, s39, v1
	s_waitcnt lgkmcnt(3)
	v_bfe_u32 v1, v22, 16, 1
	v_add3_u32 v1, v22, v1, s28
	s_waitcnt lgkmcnt(2)
	v_bfe_u32 v11, v24, 16, 1
	ds_read2_b32 v[30:31], v6 offset0:198 offset1:206
	v_lshrrev_b32_e32 v1, 16, v1
	v_add3_u32 v11, v24, v11, s28
	ds_read2_b32 v[32:33], v6 offset0:231 offset1:239
	v_and_or_b32 v13, v11, s39, v1
	s_waitcnt lgkmcnt(3)
	v_bfe_u32 v1, v26, 16, 1
	v_add3_u32 v1, v26, v1, s28
	s_waitcnt lgkmcnt(2)
; #define LAS __attribute__((address_space(3)))
; __device__ __forceinline__ unsigned f2bf(float f) { unsigned u = __builtin_bit_cast(unsigned, f); return (u + 0x7fffu + ((u >> 16) & 1u)) >> 16; }
; __device__ __forceinline__ unsigned pk2(float lo, float hi) { return f2bf(lo) | (f2bf(hi) << 16); }
; __device__ __forceinline__ void transpose_item(const float* W, int K, int N, bf16_t* WT, LAS float* scr, int item, int lane) {
;     const int nblk = N / 32, kb = item / nblk, nb = item % nblk, k0 = 64 * kb, n0 = 32 * nb;
;     float wv[32];
; #pragma unroll
;     for (int i = 0; i < 32; ++i) wv[i] = W[(size_t)(k0 + 2 * i + (lane >> 5)) * N + n0 + (lane & 31)];
; #pragma unroll
;     for (int i = 0; i < 32; ++i) scr[(2 * i + (lane >> 5)) * 33 + (lane & 31)] = wv[i];
;     asm volatile("s_waitcnt lgkmcnt(0)" ::: "memory");
;     const int c = lane & 7;
; #pragma unroll
;     for (int j = 0; j < 4; ++j) { const int n = (lane >> 3) + 8 * j; const LAS float* s = scr + (8 * c) * 33 + n;
;         u32x4 o; o.x = pk2(s[0 * 33], s[1 * 33]); o.y = pk2(s[2 * 33], s[3 * 33]); o.z = pk2(s[4 * 33], s[5 * 33]); o.w = pk2(s[6 * 33], s[7 * 33]);
;         *(u32x4*)(WT + (size_t)(n0 + n) * K + k0 + 8 * c) = o; }
;     asm volatile("s_waitcnt lgkmcnt(0)" ::: "memory");
	v_bfe_u32 v11, v28, 16, 1
	v_lshrrev_b32_e32 v1, 16, v1
	v_add3_u32 v11, v28, v11, s28
	v_and_or_b32 v14, v11, s39, v1
	s_waitcnt lgkmcnt(1)
	v_bfe_u32 v1, v30, 16, 1
	v_add3_u32 v1, v30, v1, s28
	s_waitcnt lgkmcnt(0)
	v_bfe_u32 v11, v32, 16, 1
	v_lshrrev_b32_e32 v1, 16, v1
	v_add3_u32 v11, v32, v11, s28
	v_and_or_b32 v15, v11, s39, v1
	v_or_b32_e32 v1, s22, v5
	v_mul_lo_u32 v11, s59, v1
	v_mad_u64_u32 v[34:35], s[44:45], s58, v1, 0
	s_mul_i32 s34, s58, s23
	v_bfe_u32 v1, v17, 16, 1
	v_add3_u32 v35, v35, s34, v11
	v_add3_u32 v1, v17, v1, s28
	v_bfe_u32 v11, v21, 16, 1
	v_lshl_add_u64 v[34:35], v[34:35], 1, v[18:19]
	v_lshrrev_b32_e32 v1, 16, v1
	v_add3_u32 v11, v21, v11, s28
	global_store_dwordx4 v[34:35], v[12:15], off nt
	ds_read2_b32 v[20:21], v6 offset0:16 offset1:24
	s_add_i32 s36, s36, s26
	v_and_or_b32 v12, v11, s39, v1
	v_bfe_u32 v1, v23, 16, 1
	v_add3_u32 v1, v23, v1, s28
	v_bfe_u32 v11, v25, 16, 1
	v_lshrrev_b32_e32 v1, 16, v1
	v_add3_u32 v11, v25, v11, s28
	v_and_or_b32 v13, v11, s39, v1
	v_bfe_u32 v1, v27, 16, 1
	v_add3_u32 v1, v27, v1, s28
	v_bfe_u32 v11, v29, 16, 1
	v_lshrrev_b32_e32 v1, 16, v1
	v_add3_u32 v11, v29, v11, s28
	v_and_or_b32 v14, v11, s39, v1
	v_bfe_u32 v1, v31, 16, 1
	v_add3_u32 v1, v31, v1, s28
	v_bfe_u32 v11, v33, 16, 1
	v_lshrrev_b32_e32 v1, 16, v1
	v_add3_u32 v11, v33, v11, s28
	v_and_or_b32 v15, v11, s39, v1
	v_or_b32_e32 v1, s22, v7
	v_mul_lo_u32 v11, s59, v1
	v_mad_u64_u32 v[16:17], s[44:45], s58, v1, 0
	v_add3_u32 v17, v17, s34, v11
	v_lshl_add_u64 v[16:17], v[16:17], 1, v[18:19]
	global_store_dwordx4 v[16:17], v[12:15], off nt
	ds_read2_b32 v[16:17], v6 offset0:49 offset1:57
	ds_read2_b32 v[22:23], v6 offset0:82 offset1:90
	ds_read2_b32 v[24:25], v6 offset0:115 offset1:123
	s_waitcnt lgkmcnt(3)
	v_bfe_u32 v1, v20, 16, 1
	v_add3_u32 v1, v20, v1, s28
	s_waitcnt lgkmcnt(2)
	v_bfe_u32 v11, v16, 16, 1
	ds_read2_b32 v[26:27], v6 offset0:148 offset1:156
	v_lshrrev_b32_e32 v1, 16, v1
	v_add3_u32 v11, v16, v11, s28
	ds_read2_b32 v[28:29], v6 offset0:181 offset1:189
	v_and_or_b32 v12, v11, s39, v1
	s_waitcnt lgkmcnt(3)
	v_bfe_u32 v1, v22, 16, 1
	v_add3_u32 v1, v22, v1, s28
	s_waitcnt lgkmcnt(2)
	v_bfe_u32 v11, v24, 16, 1
	ds_read2_b32 v[30:31], v6 offset0:214 offset1:222
	v_lshrrev_b32_e32 v1, 16, v1
	v_add3_u32 v11, v24, v11, s28
	ds_read2_b32 v[32:33], v6 offset0:247 offset1:255
	v_and_or_b32 v13, v11, s39, v1
	s_waitcnt lgkmcnt(3)
	v_bfe_u32 v1, v26, 16, 1
	v_add3_u32 v1, v26, v1, s28
	s_waitcnt lgkmcnt(2)
	v_bfe_u32 v11, v28, 16, 1
	v_lshrrev_b32_e32 v1, 16, v1
	v_add3_u32 v11, v28, v11, s28
	v_and_or_b32 v14, v11, s39, v1
	s_waitcnt lgkmcnt(1)
	v_bfe_u32 v1, v30, 16, 1
	v_add3_u32 v1, v30, v1, s28
	s_waitcnt lgkmcnt(0)
	v_bfe_u32 v11, v32, 16, 1
	v_lshrrev_b32_e32 v1, 16, v1
	v_add3_u32 v11, v32, v11, s28
	v_and_or_b32 v15, v11, s39, v1
	v_or_b32_e32 v1, s22, v8
	v_mul_lo_u32 v11, s59, v1
	v_mad_u64_u32 v[34:35], s[44:45], s58, v1, 0
	v_bfe_u32 v1, v21, 16, 1
	v_add3_u32 v35, v35, s34, v11
	v_add3_u32 v1, v21, v1, s28
	v_bfe_u32 v11, v17, 16, 1
	v_lshl_add_u64 v[34:35], v[34:35], 1, v[18:19]
	v_lshrrev_b32_e32 v1, 16, v1
	v_add3_u32 v11, v17, v11, s28
	global_store_dwordx4 v[34:35], v[12:15], off nt
	s_cmpk_lt_i32 s36, 0x1880
	s_nop 0
	v_and_or_b32 v12, v11, s39, v1
	v_bfe_u32 v1, v23, 16, 1
	v_add3_u32 v1, v23, v1, s28
	v_bfe_u32 v11, v25, 16, 1
	v_lshrrev_b32_e32 v1, 16, v1
	v_add3_u32 v11, v25, v11, s28
	v_and_or_b32 v13, v11, s39, v1
	v_bfe_u32 v1, v27, 16, 1
	v_add3_u32 v1, v27, v1, s28
	v_bfe_u32 v11, v29, 16, 1
	v_lshrrev_b32_e32 v1, 16, v1
	v_add3_u32 v11, v29, v11, s28
	v_and_or_b32 v14, v11, s39, v1
	v_bfe_u32 v1, v31, 16, 1
	v_add3_u32 v1, v31, v1, s28
	v_bfe_u32 v11, v33, 16, 1
	v_lshrrev_b32_e32 v1, 16, v1
	v_add3_u32 v11, v33, v11, s28
	v_and_or_b32 v15, v11, s39, v1
	v_or_b32_e32 v1, s22, v9
	v_mul_lo_u32 v11, s59, v1
	v_mad_u64_u32 v[16:17], s[22:23], s58, v1, 0
	v_add3_u32 v17, v17, s34, v11
	v_lshl_add_u64 v[16:17], v[16:17], 1, v[18:19]
	global_store_dwordx4 v[16:17], v[12:15], off nt
	s_waitcnt lgkmcnt(0)
	s_cbranch_scc0 .LBB0_1208

; __device__ __forceinline__ void transpose_item(const float* W, int K, int N, bf16_t* WT, LAS float* scr, int item, int lane) {
;     const int nblk = N / 32, kb = item / nblk, nb = item % nblk, k0 = 64 * kb, n0 = 32 * nb;
;     float wv[32];
; #pragma unroll
;     for (int i = 0; i < 32; ++i) wv[i] = W[(size_t)(k0 + 2 * i + (lane >> 5)) * N + n0 + (lane & 31)];
.LBB0_1221:
	s_lshr_b32 s22, s34, 5
	v_cvt_f32_u32_e32 v1, s22
	s_sub_i32 s78, 0, s22
	s_abs_i32 s74, s75
	s_ashr_i32 s23, s75, 31
	v_rcp_iflag_f32_e32 v1, v1
	s_nop 0
	v_mul_f32_e32 v1, 0x4f7ffffe, v1
	v_cvt_u32_f32_e32 v1, v1
	s_nop 0
	v_readfirstlane_b32 s79, v1
	s_mul_i32 s78, s78, s79
	s_mul_hi_u32 s78, s79, s78
	s_add_i32 s79, s79, s78
	s_mul_hi_u32 s78, s74, s79
	s_mul_i32 s79, s78, s22
	s_sub_i32 s74, s74, s79
	s_add_i32 s80, s78, 1
	s_sub_i32 s79, s74, s22
	s_cmp_ge_u32 s74, s22
	s_cselect_b32 s78, s80, s78
	s_cselect_b32 s74, s79, s74
	s_add_i32 s79, s78, 1
	s_cmp_ge_u32 s74, s22
	s_cselect_b32 s74, s79, s78
	s_xor_b32 s74, s74, s23
	s_sub_i32 s23, s74, s23
	s_mul_i32 s22, s23, s22
	s_sub_i32 s22, s75, s22
	s_lshl_b32 s22, s22, 5
	s_lshl_b32 s74, s23, 6
	s_ashr_i32 s23, s22, 31
	s_lshl_b64 s[78:79], s[22:23], 2
	v_or_b32_e32 v1, s74, v2
	s_add_u32 s72, s72, s78
	s_addc_u32 s73, s73, s79
	s_ashr_i32 s75, s74, 31
	v_or_b32_e32 v14, 2, v1
	v_or_b32_e32 v16, 4, v1
	v_or_b32_e32 v18, 6, v1
	v_or_b32_e32 v20, 8, v1
	v_or_b32_e32 v22, 10, v1
	v_or_b32_e32 v24, 12, v1
	v_lshl_add_u64 v[10:11], s[72:73], 0, v[96:97]
	s_mul_i32 s72, s75, s34
	v_mad_u64_u32 v[12:13], s[78:79], v1, s34, 0
	v_mad_u64_u32 v[14:15], s[78:79], v14, s34, 0
	v_mad_u64_u32 v[16:17], s[78:79], v16, s34, 0
	v_mad_u64_u32 v[18:19], s[78:79], v18, s34, 0
	v_mad_u64_u32 v[20:21], s[78:79], v20, s34, 0
	v_mad_u64_u32 v[22:23], s[78:79], v22, s34, 0
	v_mad_u64_u32 v[24:25], s[78:79], v24, s34, 0
	v_or_b32_e32 v26, 14, v1
	v_add_u32_e32 v13, s72, v13
	v_add_u32_e32 v15, s72, v15
	v_add_u32_e32 v17, s72, v17
	v_add_u32_e32 v19, s72, v19
	v_add_u32_e32 v21, s72, v21
	v_add_u32_e32 v23, s72, v23
	v_add_u32_e32 v25, s72, v25
	v_mad_u64_u32 v[26:27], s[78:79], v26, s34, 0
	v_lshl_add_u64 v[12:13], v[12:13], 2, v[10:11]
	v_lshl_add_u64 v[14:15], v[14:15], 2, v[10:11]
	v_lshl_add_u64 v[16:17], v[16:17], 2, v[10:11]
	v_lshl_add_u64 v[18:19], v[18:19], 2, v[10:11]
	v_lshl_add_u64 v[20:21], v[20:21], 2, v[10:11]
	v_lshl_add_u64 v[22:23], v[22:23], 2, v[10:11]
	v_lshl_add_u64 v[24:25], v[24:25], 2, v[10:11]
	v_add_u32_e32 v27, s72, v27
	v_lshl_add_u64 v[26:27], v[26:27], 2, v[10:11]
	global_load_dword v28, v[12:13], off nt
	global_load_dword v29, v[14:15], off nt
	global_load_dword v30, v[16:17], off nt
	global_load_dword v31, v[18:19], off nt
	global_load_dword v32, v[20:21], off nt
	global_load_dword v33, v[22:23], off nt
	global_load_dword v34, v[24:25], off nt
	global_load_dword v35, v[26:27], off nt
	v_or_b32_e32 v12, 16, v1
	v_or_b32_e32 v14, 18, v1
	v_or_b32_e32 v16, 20, v1
	v_or_b32_e32 v18, 22, v1
	v_or_b32_e32 v20, 24, v1
	v_or_b32_e32 v22, 26, v1
	v_or_b32_e32 v24, 28, v1
	v_mad_u64_u32 v[12:13], s[78:79], v12, s34, 0
	v_mad_u64_u32 v[14:15], s[78:79], v14, s34, 0
	v_mad_u64_u32 v[16:17], s[78:79], v16, s34, 0
	v_mad_u64_u32 v[18:19], s[78:79], v18, s34, 0
	v_mad_u64_u32 v[20:21], s[78:79], v20, s34, 0
	v_mad_u64_u32 v[22:23], s[78:79], v22, s34, 0
	v_mad_u64_u32 v[24:25], s[78:79], v24, s34, 0
	v_or_b32_e32 v26, 30, v1
	v_add_u32_e32 v13, s72, v13
	v_add_u32_e32 v15, s72, v15
	v_add_u32_e32 v17, s72, v17
	v_add_u32_e32 v19, s72, v19
	v_add_u32_e32 v21, s72, v21
	v_add_u32_e32 v23, s72, v23
	v_add_u32_e32 v25, s72, v25
	v_mad_u64_u32 v[26:27], s[78:79], v26, s34, 0
	v_lshl_add_u64 v[12:13], v[12:13], 2, v[10:11]
	v_lshl_add_u64 v[14:15], v[14:15], 2, v[10:11]
	v_lshl_add_u64 v[16:17], v[16:17], 2, v[10:11]
	v_lshl_add_u64 v[18:19], v[18:19], 2, v[10:11]
	v_lshl_add_u64 v[20:21], v[20:21], 2, v[10:11]
	v_lshl_add_u64 v[22:23], v[22:23], 2, v[10:11]
	v_lshl_add_u64 v[24:25], v[24:25], 2, v[10:11]
	v_add_u32_e32 v27, s72, v27
	v_lshl_add_u64 v[26:27], v[26:27], 2, v[10:11]
	global_load_dword v36, v[12:13], off nt
	global_load_dword v37, v[14:15], off nt
	global_load_dword v38, v[16:17], off nt
	global_load_dword v39, v[18:19], off nt
	global_load_dword v40, v[20:21], off nt
	global_load_dword v41, v[22:23], off nt
	global_load_dword v42, v[24:25], off nt
	global_load_dword v43, v[26:27], off nt
	v_or_b32_e32 v12, 32, v1
	v_or_b32_e32 v14, 34, v1
	v_or_b32_e32 v16, 36, v1
	v_or_b32_e32 v18, 38, v1
	v_or_b32_e32 v20, 40, v1
	v_or_b32_e32 v22, 42, v1
	v_or_b32_e32 v24, 44, v1
	v_mad_u64_u32 v[12:13], s[78:79], v12, s34, 0
	v_mad_u64_u32 v[14:15], s[78:79], v14, s34, 0
	v_mad_u64_u32 v[16:17], s[78:79], v16, s34, 0
	v_mad_u64_u32 v[18:19], s[78:79], v18, s34, 0
	v_mad_u64_u32 v[20:21], s[78:79], v20, s34, 0
	v_mad_u64_u32 v[22:23], s[78:79], v22, s34, 0
	v_mad_u64_u32 v[24:25], s[78:79], v24, s34, 0
	v_or_b32_e32 v26, 46, v1
	v_add_u32_e32 v13, s72, v13
	v_add_u32_e32 v15, s72, v15
	v_add_u32_e32 v17, s72, v17
	v_add_u32_e32 v19, s72, v19
	v_add_u32_e32 v21, s72, v21
	v_add_u32_e32 v23, s72, v23
	v_add_u32_e32 v25, s72, v25
	v_mad_u64_u32 v[26:27], s[78:79], v26, s34, 0
	v_lshl_add_u64 v[12:13], v[12:13], 2, v[10:11]
	v_lshl_add_u64 v[14:15], v[14:15], 2, v[10:11]
	v_lshl_add_u64 v[16:17], v[16:17], 2, v[10:11]
	v_lshl_add_u64 v[18:19], v[18:19], 2, v[10:11]
	v_lshl_add_u64 v[20:21], v[20:21], 2, v[10:11]
	v_lshl_add_u64 v[22:23], v[22:23], 2, v[10:11]
	v_lshl_add_u64 v[24:25], v[24:25], 2, v[10:11]
	v_add_u32_e32 v27, s72, v27
	v_lshl_add_u64 v[26:27], v[26:27], 2, v[10:11]
	global_load_dword v44, v[12:13], off nt
	global_load_dword v45, v[14:15], off nt
	global_load_dword v46, v[16:17], off nt
	global_load_dword v47, v[18:19], off nt
	global_load_dword v48, v[20:21], off nt
	global_load_dword v49, v[22:23], off nt
	global_load_dword v50, v[24:25], off nt
	global_load_dword v51, v[26:27], off nt
	v_or_b32_e32 v12, 48, v1
	v_or_b32_e32 v14, 50, v1
	v_or_b32_e32 v16, 52, v1
; #define LAS __attribute__((address_space(3)))
; __device__ __forceinline__ unsigned pk2(float lo, float hi) { return f2bf(lo) | (f2bf(hi) << 16); }
; __device__ __forceinline__ void transpose_item(const float* W, int K, int N, bf16_t* WT, LAS float* scr, int item, int lane) {
;     ...
;     for (int i = 0; i < 32; ++i) wv[i] = W[(size_t)(k0 + 2 * i + (lane >> 5)) * N + n0 + (lane & 31)];
; #pragma unroll
;     for (int i = 0; i < 32; ++i) scr[(2 * i + (lane >> 5)) * 33 + (lane & 31)] = wv[i];
;     asm volatile("s_waitcnt lgkmcnt(0)" ::: "memory");
;     const int c = lane & 7;
; #pragma unroll
;     for (int j = 0; j < 4; ++j) { const int n = (lane >> 3) + 8 * j; const LAS float* s = scr + (8 * c) * 33 + n;
;         u32x4 o; o.x = pk2(s[0 * 33], s[1 * 33]); o.y = pk2(s[2 * 33], s[3 * 33]); o.z = pk2(s[4 * 33], s[5 * 33]); o.w = pk2(s[6 * 33], s[7 * 33]);
	v_or_b32_e32 v18, 54, v1
	v_or_b32_e32 v20, 56, v1
	v_or_b32_e32 v22, 58, v1
	v_or_b32_e32 v24, 60, v1
	v_or_b32_e32 v1, 62, v1
	v_mad_u64_u32 v[12:13], s[78:79], v12, s34, 0
	v_mad_u64_u32 v[14:15], s[78:79], v14, s34, 0
	v_mad_u64_u32 v[16:17], s[78:79], v16, s34, 0
	v_mad_u64_u32 v[18:19], s[78:79], v18, s34, 0
	v_mad_u64_u32 v[20:21], s[78:79], v20, s34, 0
	v_mad_u64_u32 v[22:23], s[78:79], v22, s34, 0
	v_mad_u64_u32 v[24:25], s[78:79], v24, s34, 0
	v_mad_u64_u32 v[26:27], s[78:79], v1, s34, 0
	v_add_u32_e32 v13, s72, v13
	v_add_u32_e32 v15, s72, v15
	v_add_u32_e32 v17, s72, v17
	v_add_u32_e32 v19, s72, v19
	v_add_u32_e32 v21, s72, v21
	v_add_u32_e32 v23, s72, v23
	v_add_u32_e32 v25, s72, v25
	v_add_u32_e32 v27, s72, v27
	v_lshl_add_u64 v[12:13], v[12:13], 2, v[10:11]
	v_lshl_add_u64 v[14:15], v[14:15], 2, v[10:11]
	v_lshl_add_u64 v[16:17], v[16:17], 2, v[10:11]
	v_lshl_add_u64 v[18:19], v[18:19], 2, v[10:11]
	v_lshl_add_u64 v[20:21], v[20:21], 2, v[10:11]
	v_lshl_add_u64 v[22:23], v[22:23], 2, v[10:11]
	v_lshl_add_u64 v[24:25], v[24:25], 2, v[10:11]
	v_lshl_add_u64 v[10:11], v[26:27], 2, v[10:11]
	global_load_dword v1, v[12:13], off nt
	s_nop 0
	global_load_dword v12, v[14:15], off nt
	global_load_dword v13, v[16:17], off nt
	s_nop 0
	global_load_dword v14, v[18:19], off nt
	global_load_dword v15, v[20:21], off nt
	global_load_dword v16, v[22:23], off nt
	global_load_dword v17, v[24:25], off nt
	s_nop 0
	global_load_dword v10, v[10:11], off nt
	v_add_u32_e32 v11, 0x400, v9
	s_waitcnt vmcnt(0)
	ds_write2_b32 v9, v28, v29 offset1:66
	ds_write2_b32 v9, v30, v31 offset0:132 offset1:198
	ds_write2_b32 v11, v32, v33 offset0:8 offset1:74
	ds_write2_b32 v11, v34, v35 offset0:140 offset1:206
	v_add_u32_e32 v11, 0x800, v9
	ds_write2_b32 v11, v36, v37 offset0:16 offset1:82
	ds_write2_b32 v11, v38, v39 offset0:148 offset1:214
	v_add_u32_e32 v11, 0xc00, v9
	ds_write2_b32 v11, v40, v41 offset0:24 offset1:90
	ds_write2_b32 v11, v42, v43 offset0:156 offset1:222
	v_add_u32_e32 v11, 0x1000, v9
	ds_write2_b32 v11, v44, v45 offset0:32 offset1:98
	ds_write2_b32 v11, v46, v47 offset0:164 offset1:230
	v_add_u32_e32 v11, 0x1400, v9
	ds_write2_b32 v11, v48, v49 offset0:40 offset1:106
	ds_write2_b32 v11, v50, v51 offset0:172 offset1:238
	v_add_u32_e32 v11, 0x1800, v9
	ds_write2_b32 v11, v1, v12 offset0:48 offset1:114
	ds_write2_b32 v11, v13, v14 offset0:180 offset1:246
	v_add_u32_e32 v1, 0x1c00, v9
	ds_write2_b32 v1, v15, v16 offset0:56 offset1:122
	ds_write2_b32 v1, v17, v10 offset0:188 offset1:254
	s_waitcnt lgkmcnt(0)
	ds_read2_b32 v[14:15], v5 offset1:8
	ds_read2_b32 v[18:19], v5 offset0:33 offset1:41
	s_lshl_b64 s[72:73], s[74:75], 1
	s_add_u32 s70, s70, s72
	ds_read2_b32 v[20:21], v5 offset0:66 offset1:74
	s_addc_u32 s71, s71, s73
	v_mov_b32_e32 v1, v97
	ds_read2_b32 v[22:23], v5 offset0:99 offset1:107
	v_lshl_add_u64 v[16:17], s[70:71], 0, v[0:1]
	s_waitcnt lgkmcnt(0)
	v_bfe_u32 v1, v14, 16, 1
	v_add3_u32 v1, v14, v1, s28
	v_bfe_u32 v10, v18, 16, 1
	ds_read2_b32 v[24:25], v5 offset0:132 offset1:140
	v_lshrrev_b32_e32 v1, 16, v1
	v_add3_u32 v10, v18, v10, s28
	ds_read2_b32 v[26:27], v5 offset0:165 offset1:173
	v_and_or_b32 v10, v10, s39, v1
	v_bfe_u32 v1, v20, 16, 1
	v_add3_u32 v1, v20, v1, s28
	v_bfe_u32 v11, v22, 16, 1
	ds_read2_b32 v[28:29], v5 offset0:198 offset1:206
	v_lshrrev_b32_e32 v1, 16, v1
	v_add3_u32 v11, v22, v11, s28
	ds_read2_b32 v[30:31], v5 offset0:231 offset1:239
	v_and_or_b32 v11, v11, s39, v1
	s_waitcnt lgkmcnt(3)
	v_bfe_u32 v1, v24, 16, 1
	v_add3_u32 v1, v24, v1, s28
	s_waitcnt lgkmcnt(2)
	v_bfe_u32 v12, v26, 16, 1
	v_lshrrev_b32_e32 v1, 16, v1
	v_add3_u32 v12, v26, v12, s28
	v_and_or_b32 v12, v12, s39, v1
	s_waitcnt lgkmcnt(1)
	v_bfe_u32 v1, v28, 16, 1
	v_add3_u32 v1, v28, v1, s28
	s_waitcnt lgkmcnt(0)
; #define LAS __attribute__((address_space(3)))
; __device__ __forceinline__ unsigned pk2(float lo, float hi) { return f2bf(lo) | (f2bf(hi) << 16); }
; __device__ __forceinline__ void transpose_item(const float* W, int K, int N, bf16_t* WT, LAS float* scr, int item, int lane) {
;     ...
;     const int c = lane & 7;
; #pragma unroll
;     for (int j = 0; j < 4; ++j) { const int n = (lane >> 3) + 8 * j; const LAS float* s = scr + (8 * c) * 33 + n;
;         u32x4 o; o.x = pk2(s[0 * 33], s[1 * 33]); o.y = pk2(s[2 * 33], s[3 * 33]); o.z = pk2(s[4 * 33], s[5 * 33]); o.w = pk2(s[6 * 33], s[7 * 33]);
;         *(u32x4*)(WT + (size_t)(n0 + n) * K + k0 + 8 * c) = o; }
;     asm volatile("s_waitcnt lgkmcnt(0)" ::: "memory");
; __device__ __forceinline__ void convert_set(const __attribute__((address_space(4))) Args& a, ldsp lds, int set, int w, int nw, int wave, int lane) {
;     ...
;     for (int j = w; j < total; j += nw) {
;         int r = j, it;
;         if (r < l0) it = s0 + r; else { r -= l0;
;             if (r < l1) it = s1 + r; else { r -= l1;
;                 if (r < l2) it = s2 + r; else { r -= l2;
;                     if (r < l3) it = s3 + r; else it = s4 + (r - l3); } } }
;         transpose_flat(a, scr, it, lane);
	v_bfe_u32 v13, v30, 16, 1
	v_lshrrev_b32_e32 v1, 16, v1
	v_add3_u32 v13, v30, v13, s28
	v_and_or_b32 v13, v13, s39, v1
	v_or_b32_e32 v1, s22, v3
	v_mul_lo_u32 v14, s61, v1
	v_mad_u64_u32 v[32:33], s[70:71], s60, v1, 0
	s_mul_i32 s34, s60, s23
	v_add3_u32 v33, v33, s34, v14
	v_lshl_add_u64 v[32:33], v[32:33], 1, v[16:17]
	v_bfe_u32 v1, v15, 16, 1
	global_store_dwordx4 v[32:33], v[10:13], off nt
	v_add3_u32 v1, v15, v1, s28
	v_lshrrev_b32_e32 v1, 16, v1
	v_bfe_u32 v10, v19, 16, 1
	v_add3_u32 v10, v19, v10, s28
	v_and_or_b32 v10, v10, s39, v1
	v_bfe_u32 v1, v21, 16, 1
	v_add3_u32 v1, v21, v1, s28
	v_bfe_u32 v11, v23, 16, 1
	v_lshrrev_b32_e32 v1, 16, v1
	v_add3_u32 v11, v23, v11, s28
	v_and_or_b32 v11, v11, s39, v1
	v_bfe_u32 v1, v25, 16, 1
	v_add3_u32 v1, v25, v1, s28
	v_bfe_u32 v12, v27, 16, 1
	v_lshrrev_b32_e32 v1, 16, v1
	v_add3_u32 v12, v27, v12, s28
	v_and_or_b32 v12, v12, s39, v1
	v_bfe_u32 v1, v29, 16, 1
	v_add3_u32 v1, v29, v1, s28
	v_bfe_u32 v13, v31, 16, 1
	v_lshrrev_b32_e32 v1, 16, v1
	v_add3_u32 v13, v31, v13, s28
	v_and_or_b32 v13, v13, s39, v1
	v_or_b32_e32 v1, s22, v6
	v_mul_lo_u32 v20, s61, v1
	v_mad_u64_u32 v[14:15], s[70:71], s60, v1, 0
	v_add3_u32 v15, v15, s34, v20
	ds_read2_b32 v[18:19], v5 offset0:16 offset1:24
	v_lshl_add_u64 v[14:15], v[14:15], 1, v[16:17]
	global_store_dwordx4 v[14:15], v[10:13], off nt
	ds_read2_b32 v[14:15], v5 offset0:49 offset1:57
	ds_read2_b32 v[20:21], v5 offset0:82 offset1:90
	ds_read2_b32 v[22:23], v5 offset0:115 offset1:123
	s_waitcnt lgkmcnt(3)
	v_bfe_u32 v1, v18, 16, 1
	v_add3_u32 v1, v18, v1, s28
	s_waitcnt lgkmcnt(2)
	v_bfe_u32 v10, v14, 16, 1
	ds_read2_b32 v[24:25], v5 offset0:148 offset1:156
	v_lshrrev_b32_e32 v1, 16, v1
	v_add3_u32 v10, v14, v10, s28
	ds_read2_b32 v[26:27], v5 offset0:181 offset1:189
	v_and_or_b32 v10, v10, s39, v1
	s_waitcnt lgkmcnt(3)
	v_bfe_u32 v1, v20, 16, 1
	v_add3_u32 v1, v20, v1, s28
	s_waitcnt lgkmcnt(2)
	v_bfe_u32 v11, v22, 16, 1
	ds_read2_b32 v[28:29], v5 offset0:214 offset1:222
	v_lshrrev_b32_e32 v1, 16, v1
	v_add3_u32 v11, v22, v11, s28
	ds_read2_b32 v[30:31], v5 offset0:247 offset1:255
	v_and_or_b32 v11, v11, s39, v1
	s_waitcnt lgkmcnt(3)
	v_bfe_u32 v1, v24, 16, 1
	v_add3_u32 v1, v24, v1, s28
	s_waitcnt lgkmcnt(2)
	v_bfe_u32 v12, v26, 16, 1
	v_lshrrev_b32_e32 v1, 16, v1
	v_add3_u32 v12, v26, v12, s28
	v_and_or_b32 v12, v12, s39, v1
	s_waitcnt lgkmcnt(1)
	v_bfe_u32 v1, v28, 16, 1
	v_add3_u32 v1, v28, v1, s28
	s_waitcnt lgkmcnt(0)
	v_bfe_u32 v13, v30, 16, 1
	v_lshrrev_b32_e32 v1, 16, v1
	v_add3_u32 v13, v30, v13, s28
	v_and_or_b32 v13, v13, s39, v1
	v_or_b32_e32 v1, s22, v7
	v_mul_lo_u32 v14, s61, v1
	v_mad_u64_u32 v[32:33], s[70:71], s60, v1, 0
	v_add3_u32 v33, v33, s34, v14
	v_lshl_add_u64 v[32:33], v[32:33], 1, v[16:17]
	v_bfe_u32 v1, v19, 16, 1
	global_store_dwordx4 v[32:33], v[10:13], off nt
	v_add3_u32 v1, v19, v1, s28
	v_lshrrev_b32_e32 v1, 16, v1
	v_bfe_u32 v10, v15, 16, 1
	v_add3_u32 v10, v15, v10, s28
	v_and_or_b32 v10, v10, s39, v1
	v_bfe_u32 v1, v21, 16, 1
	v_add3_u32 v1, v21, v1, s28
	v_bfe_u32 v11, v23, 16, 1
	v_lshrrev_b32_e32 v1, 16, v1
	v_add3_u32 v11, v23, v11, s28
	v_and_or_b32 v11, v11, s39, v1
	v_bfe_u32 v1, v25, 16, 1
	v_add3_u32 v1, v25, v1, s28
	v_bfe_u32 v12, v27, 16, 1
	v_lshrrev_b32_e32 v1, 16, v1
	v_add3_u32 v12, v27, v12, s28
	v_and_or_b32 v12, v12, s39, v1
	v_bfe_u32 v1, v29, 16, 1
	v_add3_u32 v1, v29, v1, s28
	v_bfe_u32 v13, v31, 16, 1
	v_lshrrev_b32_e32 v1, 16, v1
	v_add3_u32 v13, v31, v13, s28
	v_and_or_b32 v13, v13, s39, v1
	v_or_b32_e32 v1, s22, v8
	v_mul_lo_u32 v18, s61, v1
	v_mad_u64_u32 v[14:15], s[22:23], s60, v1, 0
	v_add3_u32 v15, v15, s34, v18
	v_lshl_add_u64 v[14:15], v[14:15], 1, v[16:17]
	global_store_dwordx4 v[14:15], v[10:13], off nt
	s_add_i32 s76, s76, s26
	s_waitcnt lgkmcnt(0)
	s_add_i32 s77, s77, s26
	s_add_i32 s64, s64, s26
	s_add_i32 s69, s69, s26
	s_add_i32 s68, s68, s26
	s_add_i32 s65, s65, s26
	s_add_i32 s22, s89, s76
	s_cmp_lt_i32 s22, s49
	s_cbranch_scc0 .LBB0_1210
